# rwkv2 role-2 pull distance pc+5 instead of pc+4 (v41 otherwise)
# speedup vs baseline: 1.0047x; 1.0047x over previous
; __device__ unsigned long long rwkv2_phase(const Params& p, unsigned char* smem) {
;     ...
;             for (int pc = 0; pc <= NCH + 1; ++pc) {
;                 const int cs = pc - 2; const bool act = (cs >= 0 && cs < NCH); const bool doY = act && ((cs & 1) == ws);
;                 int ln_ = lane; asm volatile("" : "+v"(ln_)); const int lane = ln_, l15 = ln_ & 15, lq = ln_ >> 4; (void)lane;
.LBB0_922:
	s_waitcnt lgkmcnt(0)
	s_barrier
	s_add_i32 s40, s30, 5
	s_cmpk_gt_u32 s40, 0xff
	s_cbranch_scc1 RWPULL_skip
	v_readlane_b32 s38, v251, 36
	v_readlane_b32 s39, v251, 37
	s_lshl_b32 s41, s40, 17
	s_mul_i32 s42, s40, 0x3000
	v_add_u32_e32 v235, s41, v244
	v_add_u32_e32 v236, s41, v245
	v_add_u32_e32 v237, s41, v246
	v_add_u32_e32 v238, s41, v247
	v_add_u32_e32 v239, s42, v248
	global_load_dwordx4 v[240:243], v235, s[38:39]
	global_load_dwordx4 v[240:243], v236, s[38:39]
	global_load_dwordx4 v[240:243], v237, s[38:39]
	global_load_dwordx4 v[240:243], v238, s[38:39]
	global_load_dwordx4 v[240:243], v239, s[38:39]
	global_load_dwordx4 v[240:243], v239, s[38:39] offset:1024
	global_load_dwordx4 v[240:243], v239, s[38:39] offset:2048
	global_load_dwordx4 v[240:243], v239, s[38:39] offset:3072
	v_add_u32_e32 v239, 0x1000, v239
	global_load_dwordx4 v[240:243], v239, s[38:39]
	global_load_dwordx4 v[240:243], v239, s[38:39] offset:1024
